# phase-1 tail: WL gather loads hoisted to the start of the tail (no per-trip vmcnt(0) round trips), on top of previous
# baseline (speedup 1.0000x reference)
; #define LAS __attribute__((address_space(3)))
; DI unsigned f2bf(float f) { unsigned u = __builtin_bit_cast(unsigned, f); return (u + 0x7fffu + ((u >> 16) & 1u)) >> 16; }
; #define P (*args_here())
; DI void p0_transposes(const Ptrs& P, LAS unsigned char* lds, int lo, int hi, int w, int NW, int wave, int lane) {
;     unsigned char* ws = P.ws;
;     LAS float* scr = (LAS float*)(lds + RING_OFF + wave * 16384);
;     for (int it = lo + w; it < hi; it += NW) {
;         int r = it;
;         if (r < 4 * P0_I_GU) {
;             const int which = r / P0_I_GU; r -= which * P0_I_GU; const int nblk = FF / 32, kb = r / nblk, nb = r % nblk;
;             const float* W = which == 0 ? P.in[9] : which == 1 ? P.in[10] : which == 2 ? P.in[32] : P.in[33];
;             bf16* WT = (bf16*)(ws + (which < 2 ? WS_WGUA : WS_WGUB));
;             p0_transpose_item(W, DM, FF, WT, kb, nb, gu_row(32 * nb, which & 1), scr, lane); continue; }
;         r -= 4 * P0_I_GU;
;         if (r < 2 * P0_I_D) { const int which = r / P0_I_D; r -= which * P0_I_D; const int nblk = DM / 32, kb = r / nblk, nb = r % nblk;
;             p0_transpose_item(which ? P.in[34] : P.in[11], FF, DM, (bf16*)(ws + (which ? WS_WDB : WS_WDA)), kb, nb, 32 * nb, scr, lane); continue; }
; DI void p0_small(const Ptrs& P, int gt, int NGT) {
;     ...
;     { bf16* WL = (bf16*)(ws + WS_WL); const float* wl = P.in[20]; const float* al = P.in[22]; const float* gl = P.in[23];
;       for (int i = gt; i < 1536 * 256; i += NGT) { const int n = i >> 8, k = i & 255; float v = 0.f;
;           if (n < 512) { if (k < 64) v = wl[k * 512 + n]; }
;           else if (n < 1024) { if (k >= 64 && k < 128) v = al[(k - 64) * 512 + (n - 512)]; }
;           else { if (k >= 128) v = gl[(k - 128) * 512 + (n - 1024)]; }
;           WL[i] = (bf16)f2bf(v); } }
.LBB0_92:
	s_mov_b64 s[2:3], s[96:97]
	s_cmpk_lt_i32 s33, 0x58
	s_cbranch_scc1 .LBB0_142
	s_add_i32 s98, s33, 0xffffffa8
	s_load_dwordx2 s[8:9], s[96:97], 0xa0
	s_load_dwordx4 s[12:15], s[96:97], 0xb0
	v_lshl_or_b32 v245, s98, 9, v0
	v_and_b32_e32 v246, 0xff, v0
	v_lshrrev_b32_e32 v247, 8, v245
	v_lshl_add_u32 v247, v246, 9, v247
	v_lshlrev_b32_e32 v247, 2, v247
	v_lshrrev_b32_e32 v246, 6, v246
	v_min_u32_e32 v246, 2, v246
	v_add_u32_e32 v249, 0x1500, v247
	v_cmp_eq_u32_e32 vcc, 0, v246
	s_mov_b64 s[18:19], vcc
	v_cmp_eq_u32_e32 vcc, 1, v246
	s_mov_b64 s[20:21], vcc
	v_cmp_eq_u32_e32 vcc, 2, v246
	s_mov_b64 s[22:23], vcc
	s_waitcnt lgkmcnt(0)
	s_add_u32 s12, s12, 0xfffdf800
	s_addc_u32 s13, s13, -1
	s_add_u32 s14, s14, 0xfffbf000
	s_addc_u32 s15, s15, -1
	v_lshrrev_b32_e32 v248, 17, v245
	v_mov_b32_e32 v240, 0
	v_cmp_eq_u32_e32 vcc, 0, v248
	s_and_b64 vcc, vcc, s[18:19]
	s_and_saveexec_b64 s[16:17], vcc
	s_cbranch_execz .Lmy_wl_00
	global_load_dword v240, v247, s[8:9] offset:0
.Lmy_wl_00:
	s_mov_b64 exec, s[16:17]
	v_cmp_eq_u32_e32 vcc, 1, v248
	s_and_b64 vcc, vcc, s[20:21]
	s_and_saveexec_b64 s[16:17], vcc
	s_cbranch_execz .Lmy_wl_01
	global_load_dword v240, v247, s[12:13] offset:0
.Lmy_wl_01:
	s_mov_b64 exec, s[16:17]
	v_cmp_eq_u32_e32 vcc, 2, v248
	s_and_b64 vcc, vcc, s[22:23]
	s_and_saveexec_b64 s[16:17], vcc
	s_cbranch_execz .Lmy_wl_02
	global_load_dword v240, v247, s[14:15] offset:0
.Lmy_wl_02:
	s_mov_b64 exec, s[16:17]
	v_add_u32_e32 v248, 0x15000, v245
	v_lshrrev_b32_e32 v248, 17, v248
	v_mov_b32_e32 v241, 0
	v_cmp_eq_u32_e32 vcc, 0, v248
	s_and_b64 vcc, vcc, s[18:19]
	s_and_saveexec_b64 s[16:17], vcc
	s_cbranch_execz .Lmy_wl_10
	global_load_dword v241, v247, s[8:9] offset:1344
.Lmy_wl_10:
	s_mov_b64 exec, s[16:17]
	v_cmp_eq_u32_e32 vcc, 1, v248
	s_and_b64 vcc, vcc, s[20:21]
	s_and_saveexec_b64 s[16:17], vcc
	s_cbranch_execz .Lmy_wl_11
	global_load_dword v241, v247, s[12:13] offset:1344
.Lmy_wl_11:
	s_mov_b64 exec, s[16:17]
	v_cmp_eq_u32_e32 vcc, 2, v248
	s_and_b64 vcc, vcc, s[22:23]
	s_and_saveexec_b64 s[16:17], vcc
	s_cbranch_execz .Lmy_wl_12
	global_load_dword v241, v247, s[14:15] offset:1344
.Lmy_wl_12:
	s_mov_b64 exec, s[16:17]
	v_add_u32_e32 v248, 0x2a000, v245
	v_lshrrev_b32_e32 v248, 17, v248
	v_mov_b32_e32 v242, 0
	v_cmp_eq_u32_e32 vcc, 0, v248
	s_and_b64 vcc, vcc, s[18:19]
	s_and_saveexec_b64 s[16:17], vcc
	s_cbranch_execz .Lmy_wl_20
	global_load_dword v242, v247, s[8:9] offset:2688
.Lmy_wl_20:
	s_mov_b64 exec, s[16:17]
	v_cmp_eq_u32_e32 vcc, 1, v248
	s_and_b64 vcc, vcc, s[20:21]
	s_and_saveexec_b64 s[16:17], vcc
	s_cbranch_execz .Lmy_wl_21
	global_load_dword v242, v247, s[12:13] offset:2688
.Lmy_wl_21:
	s_mov_b64 exec, s[16:17]
	v_cmp_eq_u32_e32 vcc, 2, v248
	s_and_b64 vcc, vcc, s[22:23]
	s_and_saveexec_b64 s[16:17], vcc
	s_cbranch_execz .Lmy_wl_22
	global_load_dword v242, v247, s[14:15] offset:2688
.Lmy_wl_22:
	s_mov_b64 exec, s[16:17]
	v_add_u32_e32 v248, 0x3f000, v245
	v_lshrrev_b32_e32 v248, 17, v248
	v_mov_b32_e32 v243, 0
	v_cmp_eq_u32_e32 vcc, 0, v248
	s_and_b64 vcc, vcc, s[18:19]
	s_and_saveexec_b64 s[16:17], vcc
	s_cbranch_execz .Lmy_wl_30
	global_load_dword v243, v247, s[8:9] offset:4032
.Lmy_wl_30:
	s_mov_b64 exec, s[16:17]
	v_cmp_eq_u32_e32 vcc, 1, v248
	s_and_b64 vcc, vcc, s[20:21]
	s_and_saveexec_b64 s[16:17], vcc
	s_cbranch_execz .Lmy_wl_31
	global_load_dword v243, v247, s[12:13] offset:4032
.Lmy_wl_31:
	s_mov_b64 exec, s[16:17]
	v_cmp_eq_u32_e32 vcc, 2, v248
	s_and_b64 vcc, vcc, s[22:23]
	s_and_saveexec_b64 s[16:17], vcc
	s_cbranch_execz .Lmy_wl_32
	global_load_dword v243, v247, s[14:15] offset:4032
.Lmy_wl_32:
	s_mov_b64 exec, s[16:17]
	v_add_u32_e32 v248, 0x54000, v245
	v_lshrrev_b32_e32 v248, 17, v248
	v_mov_b32_e32 v244, 0
	v_cmp_eq_u32_e32 vcc, 0, v248
	s_and_b64 vcc, vcc, s[18:19]
	s_and_saveexec_b64 s[16:17], vcc
	s_cbranch_execz .Lmy_wl_40
	global_load_dword v244, v249, s[8:9]
.Lmy_wl_40:
	s_mov_b64 exec, s[16:17]
	v_cmp_eq_u32_e32 vcc, 1, v248
	s_and_b64 vcc, vcc, s[20:21]
	s_and_saveexec_b64 s[16:17], vcc
	s_cbranch_execz .Lmy_wl_41
	global_load_dword v244, v249, s[12:13]
.Lmy_wl_41:
	s_mov_b64 exec, s[16:17]
	v_cmp_eq_u32_e32 vcc, 2, v248
	s_and_b64 vcc, vcc, s[22:23]
	s_and_saveexec_b64 s[16:17], vcc
	s_cbranch_execz .Lmy_wl_42
	global_load_dword v244, v249, s[14:15]
.Lmy_wl_42:
	s_mov_b64 exec, s[16:17]
	s_add_i32 s0, s33, 0xffffffa8
	s_load_dwordx2 s[4:5], s[2:3], 0x130
	s_lshl_b32 s1, s0, 3
	v_readlane_b32 s6, v254, 9
	s_add_i32 s1, s6, s1
	s_add_i32 s6, s1, 0x1600
	s_cmpk_gt_i32 s6, 0x1b7f
	v_readlane_b32 s7, v254, 10
	s_cbranch_scc1 .LBB0_100
	s_load_dwordx2 s[8:9], s[2:3], 0x58
	v_readlane_b32 s6, v254, 9
	v_lshlrev_b32_e32 v4, 3, v0
	s_lshl_b32 s6, s6, 14
	v_and_b32_e32 v8, 31, v0
	v_lshrrev_b32_e32 v10, 3, v186
	v_and_b32_e32 v16, 56, v4
	s_add_i32 s6, s6, 0
	v_mov_b32_e32 v3, 0
	v_lshlrev_b32_e32 v2, 2, v8
	v_mul_u32_u24_e32 v4, 0x84, v16
	v_lshlrev_b32_e32 v5, 2, v10
	v_lshrrev_b32_e32 v1, 5, v186
	v_add_u32_e32 v9, s6, v2
	v_add3_u32 v11, s6, v4, v5
	s_waitcnt lgkmcnt(0)
	v_lshl_add_u64 v[4:5], s[8:9], 0, v[2:3]
	v_lshlrev_b32_e32 v2, 1, v16
	v_mul_u32_u24_e32 v15, 0x84, v1
	v_lshl_add_u64 v[6:7], s[4:5], 0, v[2:3]
	s_mov_b64 s[8:9], 0xd00000
	v_readlane_b32 s7, v254, 10
	v_lshl_add_u64 v[6:7], v[6:7], 0, s[8:9]
	v_readlane_b32 s8, v254, 11
	v_add_u32_e32 v15, v9, v15
	s_mov_b32 s7, 0
	v_or_b32_e32 v12, 8, v10
	v_or_b32_e32 v13, 16, v10
	v_or_b32_e32 v14, 24, v10
	s_lshl_b32 s10, s1, 1
	s_lshl_b32 s11, s1, 5
	s_add_i32 s12, s8, 0x18bf
	s_movk_i32 s13, 0x7fff
	s_mov_b32 s14, 0xffff0000
	s_movk_i32 s15, 0x100
	s_mov_b32 s16, 0x200000
	v_lshlrev_b32_e32 v2, 2, v8
	s_movk_i32 s17, 0x2c00
	v_lshlrev_b32_e32 v8, 1, v16
	v_add_u32_e32 v16, 0x400, v15
	v_add_u32_e32 v17, 0x800, v15
	v_add_u32_e32 v18, 0xc00, v15
	v_add_u32_e32 v19, 0x1000, v15
	v_add_u32_e32 v20, 0x1400, v15
	v_add_u32_e32 v21, 0x1800, v15
	v_add_u32_e32 v22, 0x1c00, v15
	v_mov_b32_e32 v23, 0xaff
	v_readlane_b32 s9, v254, 12
	s_branch .LBB0_96

; #define GAS __attribute__((address_space(1)))
; DI unsigned f2bf(float f) { unsigned u = __builtin_bit_cast(unsigned, f); return (u + 0x7fffu + ((u >> 16) & 1u)) >> 16; }
; DI unsigned pk2(float lo, float hi) { return f2bf(lo) | (f2bf(hi) << 16); }
; #define P (*args_here())
; DI void p0_small(const Ptrs& P, int gt, int NGT) {
;     ...
;     { bf16* WL = (bf16*)(ws + WS_WL); const float* wl = P.in[20]; const float* al = P.in[22]; const float* gl = P.in[23];
;       for (int i = gt; i < 1536 * 256; i += NGT) { const int n = i >> 8, k = i & 255; float v = 0.f;
;           if (n < 512) { if (k < 64) v = wl[k * 512 + n]; }
;           else if (n < 1024) { if (k >= 64 && k < 128) v = al[(k - 64) * 512 + (n - 512)]; }
;           else { if (k >= 128) v = gl[(k - 128) * 512 + (n - 1024)]; }
;           WL[i] = (bf16)f2bf(v); } }
;     { bf16* WQ = (bf16*)(ws + WS_WQ); const float* uq = P.in[14]; const float* uk = P.in[16];
;       for (int i = gt; i < 8 * 32 * 64; i += NGT) { const int cq = i & 63, rq = (i >> 6) & 31, hd = i >> 11;
;           const float* a = uq + (size_t)(4 * cq) * 768 + hd * 96; const float* b = uk + (size_t)(4 * rq) * 512 + hd * 64;
;           f32x4 acc[4];
; #pragma unroll
;           for (int rr = 0; rr < 4; ++rr) acc[rr] = (f32x4){0.f, 0.f, 0.f, 0.f};
; #pragma unroll 4
;           for (int j4 = 0; j4 < 16; ++j4) { f32x4 av[4], bv[4];
; #pragma unroll
;               for (int t = 0; t < 4; ++t) { av[t] = *(const GAS f32x4*)(a + t * 768 + 4 * j4); bv[t] = *(const GAS f32x4*)(b + t * 512 + 4 * j4); }
; #pragma unroll
;               for (int rr = 0; rr < 4; ++rr)
; #pragma unroll
;                   for (int cc = 0; cc < 4; ++cc) { const f32x4 p = av[cc] * bv[rr]; acc[rr][cc] += (p.x + p.y) + (p.z + p.w); } }
; #pragma unroll
;           for (int rr = 0; rr < 4; ++rr) *(GAS v2u*)(WQ + (size_t)(hd * 128 + 4 * rq + rr) * 256 + 4 * cq) = (v2u){pk2(acc[rr].x, acc[rr].y), pk2(acc[rr].z, acc[rr].w)}; }
.LBB0_111:
	v_lshl_or_b32 v106, s0, 9, v0
	v_lshrrev_b32_e32 v1, 8, v106
	s_mov_b64 s[6:7], exec
	v_lshlrev_b32_e32 v2, 1, v106
	s_add_u32 s8, s4, 0x2d00000
	s_addc_u32 s9, s5, 0
	s_movk_i32 s24, 0x7fff
	s_waitcnt vmcnt(0)
	v_bfe_u32 v3, v240, 16, 1
	v_add3_u32 v3, v240, v3, s24
	global_store_short_d16_hi v2, v3, s[8:9]
	s_add_u32 s8, s8, 0x2a000
	s_addc_u32 s9, s9, 0
	v_bfe_u32 v4, v241, 16, 1
	v_add3_u32 v4, v241, v4, s24
	global_store_short_d16_hi v2, v4, s[8:9]
	s_add_u32 s8, s8, 0x2a000
	s_addc_u32 s9, s9, 0
	v_bfe_u32 v5, v242, 16, 1
	v_add3_u32 v5, v242, v5, s24
	global_store_short_d16_hi v2, v5, s[8:9]
	s_add_u32 s8, s8, 0x2a000
	s_addc_u32 s9, s9, 0
	v_bfe_u32 v6, v243, 16, 1
	v_add3_u32 v6, v243, v6, s24
	global_store_short_d16_hi v2, v6, s[8:9]
	s_add_u32 s8, s8, 0x2a000
	s_addc_u32 s9, s9, 0
	v_bfe_u32 v7, v244, 16, 1
	v_add3_u32 v7, v244, v7, s24
	v_cmp_gt_u32_e32 vcc, 0xc000, v106
	s_and_saveexec_b64 s[10:11], vcc
	s_cbranch_execz .Lmy_wl_st_done
	global_store_short_d16_hi v2, v7, s[8:9]
.Lmy_wl_st_done:
.LBB0_128:
	s_or_b64 exec, exec, s[6:7]
	s_load_dwordx2 s[8:9], s[2:3], 0x70
	s_waitcnt lgkmcnt(0)
	s_add_u32 s6, s4, 0x2900000
	s_movk_i32 s0, 0x4000
	s_addc_u32 s7, s5, 0
	v_cmp_gt_u32_e32 vcc, s0, v106
	v_lshlrev_b32_e32 v132, 2, v106
	s_and_saveexec_b64 s[10:11], vcc
	s_cbranch_execz .LBB0_132
	s_load_dwordx2 s[0:1], s[2:3], 0x80
	v_lshrrev_b32_e32 v107, 11, v106
	v_lshrrev_b32_e32 v2, 4, v106
	v_and_b32_e32 v134, 0xfc, v132
	v_mul_u32_u24_e32 v4, 0x60, v107
	v_and_b32_e32 v133, 0x7c, v2
	s_movk_i32 s12, 0xc00
	v_mov_b64_e32 v[2:3], s[8:9]
	v_mad_u64_u32 v[2:3], s[12:13], v134, s12, v[2:3]
	v_lshlrev_b32_e32 v112, 2, v4
	v_mov_b32_e32 v113, 0
	v_lshl_add_u64 v[108:109], v[2:3], 0, v[112:113]
	v_lshlrev_b32_e32 v112, 11, v133
	s_waitcnt lgkmcnt(0)
	v_lshl_add_u64 v[2:3], s[0:1], 0, v[112:113]
	v_lshlrev_b32_e32 v112, 8, v107
	v_lshl_add_u64 v[110:111], v[2:3], 0, v[112:113]
	s_mov_b64 s[12:13], 0
	s_mov_b64 s[14:15], 0x1800
	s_movk_i32 s0, 0x1000
	s_mov_b64 s[16:17], 0x1000
	s_mov_b64 s[18:19], 0x2400
	s_movk_i32 s1, 0x2000
	v_mov_b32_e32 v112, v113
	v_mov_b32_e32 v114, v113
	v_mov_b32_e32 v115, v113
	v_mov_b32_e32 v118, v113
	v_mov_b32_e32 v119, v113
	v_mov_b32_e32 v116, v113
	v_mov_b32_e32 v117, v113
	v_mov_b32_e32 v122, v113
	v_mov_b32_e32 v123, v113
	v_mov_b32_e32 v120, v113
	v_mov_b32_e32 v121, v113
	v_mov_b32_e32 v124, v113
	v_mov_b32_e32 v125, v113
	v_mov_b32_e32 v126, v113
	v_mov_b32_e32 v127, v113
